# attention: NEG score fill only on skipped tiles; O stage uses v_pk_mul + v_cvt_pk_bf16 (RNE, bit-identical) instead of integer bit trick
# speedup vs baseline: 1.0077x; 1.0077x over previous
.Lattn_neg0:
	v_mov_b32_e32 v50, 0xf149f2ca
	v_mov_b32_e32 v51, 0xf149f2ca
	v_mov_b32_e32 v52, 0xf149f2ca
	v_mov_b32_e32 v53, 0xf149f2ca
	v_mov_b32_e32 v54, 0xf149f2ca
	v_mov_b32_e32 v55, 0xf149f2ca
	v_mov_b32_e32 v56, 0xf149f2ca
	v_mov_b32_e32 v57, 0xf149f2ca
	v_mov_b32_e32 v58, 0xf149f2ca
	v_mov_b32_e32 v59, 0xf149f2ca
	v_mov_b32_e32 v60, 0xf149f2ca
	v_mov_b32_e32 v61, 0xf149f2ca
	v_mov_b32_e32 v62, 0xf149f2ca
	v_mov_b32_e32 v63, 0xf149f2ca
	v_mov_b32_e32 v64, 0xf149f2ca
	v_mov_b32_e32 v65, 0xf149f2ca
	s_branch .LBB0_166
.Lattn_neg1:
	v_mov_b32_e32 v2, 0xf149f2ca
	v_mov_b32_e32 v3, 0xf149f2ca
	v_mov_b32_e32 v4, 0xf149f2ca
	v_mov_b32_e32 v5, 0xf149f2ca
	v_mov_b32_e32 v6, 0xf149f2ca
	v_mov_b32_e32 v7, 0xf149f2ca
	v_mov_b32_e32 v8, 0xf149f2ca
	v_mov_b32_e32 v9, 0xf149f2ca
	v_mov_b32_e32 v10, 0xf149f2ca
	v_mov_b32_e32 v11, 0xf149f2ca
	v_mov_b32_e32 v12, 0xf149f2ca
	v_mov_b32_e32 v13, 0xf149f2ca
	v_mov_b32_e32 v14, 0xf149f2ca
	v_mov_b32_e32 v15, 0xf149f2ca
	v_mov_b32_e32 v16, 0xf149f2ca
	v_mov_b32_e32 v17, 0xf149f2ca
	s_branch .LBB0_168
.Lattn_neg2:
	v_mov_b32_e32 v34, 0xf149f2ca
	v_mov_b32_e32 v35, 0xf149f2ca
	v_mov_b32_e32 v36, 0xf149f2ca
	v_mov_b32_e32 v37, 0xf149f2ca
	v_mov_b32_e32 v38, 0xf149f2ca
	v_mov_b32_e32 v39, 0xf149f2ca
	v_mov_b32_e32 v40, 0xf149f2ca
	v_mov_b32_e32 v41, 0xf149f2ca
	v_mov_b32_e32 v42, 0xf149f2ca
	v_mov_b32_e32 v43, 0xf149f2ca
	v_mov_b32_e32 v44, 0xf149f2ca
	v_mov_b32_e32 v45, 0xf149f2ca
	v_mov_b32_e32 v46, 0xf149f2ca
	v_mov_b32_e32 v47, 0xf149f2ca
	v_mov_b32_e32 v48, 0xf149f2ca
	v_mov_b32_e32 v49, 0xf149f2ca
	s_branch .LBB0_170
.Lattn_neg3:
	v_mov_b32_e32 v18, 0xf149f2ca
	v_mov_b32_e32 v19, 0xf149f2ca
	v_mov_b32_e32 v20, 0xf149f2ca
	v_mov_b32_e32 v21, 0xf149f2ca
	v_mov_b32_e32 v22, 0xf149f2ca
	v_mov_b32_e32 v23, 0xf149f2ca
	v_mov_b32_e32 v24, 0xf149f2ca
	v_mov_b32_e32 v25, 0xf149f2ca
	v_mov_b32_e32 v26, 0xf149f2ca
	v_mov_b32_e32 v27, 0xf149f2ca
	v_mov_b32_e32 v28, 0xf149f2ca
	v_mov_b32_e32 v29, 0xf149f2ca
	v_mov_b32_e32 v30, 0xf149f2ca
	v_mov_b32_e32 v31, 0xf149f2ca
	v_mov_b32_e32 v32, 0xf149f2ca
	v_mov_b32_e32 v33, 0xf149f2ca
	s_branch .LBB0_172
.Lattn_neg4:
	v_mov_b32_e32 v66, 0xf149f2ca
	v_mov_b32_e32 v67, 0xf149f2ca
	v_mov_b32_e32 v68, 0xf149f2ca
	v_mov_b32_e32 v69, 0xf149f2ca
	v_mov_b32_e32 v70, 0xf149f2ca
	v_mov_b32_e32 v71, 0xf149f2ca
	v_mov_b32_e32 v72, 0xf149f2ca
	v_mov_b32_e32 v73, 0xf149f2ca
	v_mov_b32_e32 v74, 0xf149f2ca
	v_mov_b32_e32 v75, 0xf149f2ca
	v_mov_b32_e32 v76, 0xf149f2ca
	v_mov_b32_e32 v77, 0xf149f2ca
	v_mov_b32_e32 v78, 0xf149f2ca
	v_mov_b32_e32 v79, 0xf149f2ca
	v_mov_b32_e32 v80, 0xf149f2ca
	v_mov_b32_e32 v81, 0xf149f2ca
	s_branch .LBB0_174

.LBB0_164:
	s_lshl_b32 s25, s22, 8
	s_add_i32 s25, s25, s23
	s_ashr_i32 s6, s25, 5
	s_sub_i32 s6, 4, s6
	s_cmpk_lt_i32 s25, 0x80
	s_cselect_b32 s19, s6, 0
	s_cmp_lt_i32 s19, 1
	s_cselect_b64 s[76:77], -1, 0
	s_cmp_gt_i32 s19, 0
	s_cbranch_scc1 .Lattn_neg0
	ds_read_b128 v[4:7], v221
	s_waitcnt vmcnt(3) lgkmcnt(0)
	v_mfma_f32_32x32x16_bf16 v[50:65], v[4:7], v[130:133], 0
	ds_read_b128 v[4:7], v222
	s_waitcnt vmcnt(2) lgkmcnt(0)
	v_mfma_f32_32x32x16_bf16 v[50:65], v[4:7], v[134:137], v[50:65]
	ds_read_b128 v[4:7], v223
	s_waitcnt vmcnt(1) lgkmcnt(0)
	v_mfma_f32_32x32x16_bf16 v[50:65], v[4:7], v[138:141], v[50:65]
	ds_read_b128 v[4:7], v224
	s_waitcnt vmcnt(0) lgkmcnt(0)
	v_mfma_f32_32x32x16_bf16 v[50:65], v[4:7], v[142:145], v[50:65]
.LBB0_166:
	s_cmp_lt_i32 s19, 2
	s_cselect_b64 s[6:7], -1, 0
	s_cmp_gt_i32 s19, 1
	s_cbranch_scc1 .Lattn_neg1
	ds_read_b128 v[2:5], v221 offset:4096
	ds_read_b128 v[18:21], v222 offset:4096
	s_waitcnt vmcnt(3) lgkmcnt(1)
	v_mfma_f32_32x32x16_bf16 v[2:17], v[2:5], v[130:133], 0
	s_waitcnt vmcnt(2) lgkmcnt(0)
	v_mfma_f32_32x32x16_bf16 v[2:17], v[18:21], v[134:137], v[2:17]
	ds_read_b128 v[18:21], v223 offset:4096
	s_waitcnt vmcnt(1) lgkmcnt(0)
	v_mfma_f32_32x32x16_bf16 v[2:17], v[18:21], v[138:141], v[2:17]
	ds_read_b128 v[18:21], v224 offset:4096
	s_waitcnt vmcnt(0) lgkmcnt(0)
	v_mfma_f32_32x32x16_bf16 v[2:17], v[18:21], v[142:145], v[2:17]
.LBB0_168:
	s_cmp_lt_i32 s19, 3
	s_cselect_b64 s[10:11], -1, 0
	s_cmp_gt_i32 s19, 2
	s_cbranch_scc1 .Lattn_neg2
	ds_read_b128 v[20:23], v221 offset:8192
	s_waitcnt vmcnt(3) lgkmcnt(0)
	v_mfma_f32_32x32x16_bf16 v[34:49], v[20:23], v[130:133], 0
	ds_read_b128 v[20:23], v222 offset:8192
	s_waitcnt vmcnt(2) lgkmcnt(0)
	v_mfma_f32_32x32x16_bf16 v[34:49], v[20:23], v[134:137], v[34:49]
	ds_read_b128 v[20:23], v223 offset:8192
	s_waitcnt vmcnt(1) lgkmcnt(0)
	v_mfma_f32_32x32x16_bf16 v[34:49], v[20:23], v[138:141], v[34:49]
	ds_read_b128 v[20:23], v224 offset:8192
	s_waitcnt vmcnt(0) lgkmcnt(0)
	v_mfma_f32_32x32x16_bf16 v[34:49], v[20:23], v[142:145], v[34:49]
.LBB0_170:
	s_cmp_lt_i32 s19, 4
	s_cselect_b64 s[12:13], -1, 0
	s_cmp_gt_i32 s19, 3
	s_cbranch_scc1 .Lattn_neg3
	ds_read_b128 v[18:21], v221 offset:12288
	ds_read_b128 v[66:69], v222 offset:12288
	s_waitcnt vmcnt(3) lgkmcnt(1)
	v_mfma_f32_32x32x16_bf16 v[18:33], v[18:21], v[130:133], 0
	s_waitcnt vmcnt(2) lgkmcnt(0)
	v_mfma_f32_32x32x16_bf16 v[18:33], v[66:69], v[134:137], v[18:33]
	ds_read_b128 v[66:69], v223 offset:12288
	s_waitcnt vmcnt(1) lgkmcnt(0)
	v_mfma_f32_32x32x16_bf16 v[18:33], v[66:69], v[138:141], v[18:33]
	ds_read_b128 v[66:69], v224 offset:12288
	s_waitcnt vmcnt(0) lgkmcnt(0)
	v_mfma_f32_32x32x16_bf16 v[18:33], v[66:69], v[142:145], v[18:33]
.LBB0_172:
	s_cmp_lt_i32 s19, 5
	s_mov_b64 s[36:37], s[74:75]
	s_cselect_b64 s[14:15], -1, 0
	s_cmp_gt_i32 s19, 4
	s_cbranch_scc1 .Lattn_neg4
	ds_read_b128 v[66:69], v221 offset:16384
	s_waitcnt vmcnt(0)
	ds_read_b128 v[236:239], v222 offset:16384
	s_waitcnt lgkmcnt(1)
	v_mfma_f32_32x32x16_bf16 v[66:81], v[66:69], v[130:133], 0
	s_waitcnt lgkmcnt(0)
	v_mfma_f32_32x32x16_bf16 v[66:81], v[236:239], v[134:137], v[66:81]
	ds_read_b128 v[236:239], v223 offset:16384
	s_waitcnt lgkmcnt(0)
	v_mfma_f32_32x32x16_bf16 v[66:81], v[236:239], v[138:141], v[66:81]
	ds_read_b128 v[236:239], v224 offset:16384
	s_waitcnt lgkmcnt(0)
	v_mfma_f32_32x32x16_bf16 v[66:81], v[236:239], v[142:145], v[66:81]

.LBB0_221:
	s_or_b64 exec, exec, s[6:7]
	ds_read_b128 v[2:5], v186
	ds_read_b128 v[6:9], v186 offset:32
	ds_read_b128 v[10:13], v186 offset:64
	ds_read_b128 v[48:51], v186 offset:96
	s_and_b64 vcc, exec, s[74:75]
	s_waitcnt lgkmcnt(3)
	v_pk_mul_f32 v[32:33], v[32:33], v[2:3]
	v_pk_mul_f32 v[16:17], v[16:17], v[2:3]
	v_cvt_pk_bf16_f32 v1, v32, v33
	v_cvt_pk_bf16_f32 v14, v16, v17
	ds_write_b16 v191, v1
	ds_write_b16_d16_hi v192, v1
	ds_write_b16 v191, v14 offset:64
	ds_write_b16_d16_hi v192, v14 offset:64
	v_pk_mul_f32 v[34:35], v[34:35], v[4:5]
	v_pk_mul_f32 v[18:19], v[18:19], v[4:5]
	v_cvt_pk_bf16_f32 v15, v34, v35
	v_cvt_pk_bf16_f32 v52, v18, v19
	ds_write_b16 v193, v15
	ds_write_b16_d16_hi v194, v15
	ds_write_b16 v193, v52 offset:64
	ds_write_b16_d16_hi v194, v52 offset:64
	s_waitcnt lgkmcnt(10)
	v_pk_mul_f32 v[36:37], v[36:37], v[6:7]
	v_pk_mul_f32 v[20:21], v[20:21], v[6:7]
	v_cvt_pk_bf16_f32 v53, v36, v37
	v_cvt_pk_bf16_f32 v54, v20, v21
	ds_write_b16 v195, v53
	ds_write_b16_d16_hi v196, v53
	ds_write_b16 v195, v54 offset:64
	ds_write_b16_d16_hi v196, v54 offset:64
	v_pk_mul_f32 v[38:39], v[38:39], v[8:9]
	v_pk_mul_f32 v[22:23], v[22:23], v[8:9]
	v_cvt_pk_bf16_f32 v55, v38, v39
	v_cvt_pk_bf16_f32 v56, v22, v23
	ds_write_b16 v197, v55
	ds_write_b16_d16_hi v198, v55
	ds_write_b16 v197, v56 offset:64
	ds_write_b16_d16_hi v198, v56 offset:64
	s_waitcnt lgkmcnt(14)
	v_pk_mul_f32 v[40:41], v[40:41], v[10:11]
	v_pk_mul_f32 v[24:25], v[24:25], v[10:11]
	v_cvt_pk_bf16_f32 v57, v40, v41
	v_cvt_pk_bf16_f32 v58, v24, v25
	ds_write_b16 v199, v57
	ds_write_b16_d16_hi v200, v57
	ds_write_b16 v199, v58 offset:64
	ds_write_b16_d16_hi v200, v58 offset:64
	v_pk_mul_f32 v[42:43], v[42:43], v[12:13]
	v_pk_mul_f32 v[26:27], v[26:27], v[12:13]
	v_cvt_pk_bf16_f32 v59, v42, v43
	v_cvt_pk_bf16_f32 v60, v26, v27
	ds_write_b16 v201, v59
	ds_write_b16_d16_hi v202, v59
	ds_write_b16 v201, v60 offset:64
	ds_write_b16_d16_hi v202, v60 offset:64
	v_pk_mul_f32 v[44:45], v[44:45], v[48:49]
	v_pk_mul_f32 v[28:29], v[28:29], v[48:49]
	v_cvt_pk_bf16_f32 v61, v44, v45
	v_cvt_pk_bf16_f32 v62, v28, v29
	ds_write_b16 v203, v61
	ds_write_b16_d16_hi v204, v61
	ds_write_b16 v203, v62 offset:64
	ds_write_b16_d16_hi v204, v62 offset:64
	v_pk_mul_f32 v[46:47], v[46:47], v[50:51]
	v_pk_mul_f32 v[30:31], v[30:31], v[50:51]
	v_cvt_pk_bf16_f32 v63, v46, v47
	v_cvt_pk_bf16_f32 v64, v30, v31
	ds_write_b16 v205, v63
	ds_write_b16_d16_hi v206, v63
	ds_write_b16 v205, v64 offset:64
	ds_write_b16_d16_hi v206, v64 offset:64
	ds_read_b128 v[2:5], v207
	s_cbranch_vccnz .LBB0_223
	ds_read_b32 v6, v187 offset:128
	s_waitcnt lgkmcnt(1)
	s_waitcnt vmcnt(4)
	v_lshlrev_b32_e32 v8, 16, v2
	v_and_b32_e32 v9, s33, v2
	v_lshlrev_b32_e32 v10, 16, v150
	v_and_b32_e32 v11, s33, v150
	v_lshlrev_b32_e32 v12, 16, v3
	v_and_b32_e32 v13, s33, v3
	v_lshlrev_b32_e32 v14, 16, v151
	v_and_b32_e32 v15, s33, v151
	v_lshlrev_b32_e32 v48, 16, v4
	v_and_b32_e32 v49, s33, v4
	v_lshlrev_b32_e32 v50, 16, v152
	v_and_b32_e32 v51, s33, v152
	v_lshlrev_b32_e32 v52, 16, v5
	v_and_b32_e32 v53, s33, v5
	v_lshlrev_b32_e32 v54, 16, v153
	v_and_b32_e32 v55, s33, v153
	s_waitcnt lgkmcnt(0)
	v_pk_fma_f32 v[8:9], v[6:7], v[10:11], v[8:9] op_sel_hi:[0,1,1]
	v_pk_fma_f32 v[12:13], v[6:7], v[14:15], v[12:13] op_sel_hi:[0,1,1]
	v_pk_fma_f32 v[48:49], v[6:7], v[50:51], v[48:49] op_sel_hi:[0,1,1]
	v_pk_fma_f32 v[52:53], v[6:7], v[54:55], v[52:53] op_sel_hi:[0,1,1]
	v_cvt_pk_bf16_f32 v2, v8, v9
	v_cvt_pk_bf16_f32 v3, v12, v13
	v_cvt_pk_bf16_f32 v4, v48, v49
	v_cvt_pk_bf16_f32 v5, v52, v53
.LBB0_223:
	s_add_i32 s6, s28, s20
	v_add_u32_e32 v1, s6, v225
	v_lshl_add_u32 v6, v1, 10, v80
	v_mov_b32_e32 v7, v0
	v_lshl_add_u64 v[6:7], v[6:7], 1, s[88:89]
	s_waitcnt lgkmcnt(0)
	global_store_dwordx4 v[6:7], v[2:5], off sc1
	s_nop 1
	ds_read_b128 v[2:5], v208
	s_and_b64 vcc, exec, s[74:75]
	s_cbranch_vccnz .LBB0_225
	ds_read_b32 v6, v187 offset:160
	s_waitcnt lgkmcnt(1)
	s_waitcnt vmcnt(3)
	v_lshlrev_b32_e32 v8, 16, v2
	v_and_b32_e32 v9, s33, v2
	v_lshlrev_b32_e32 v10, 16, v146
	v_and_b32_e32 v11, s33, v146
	v_lshlrev_b32_e32 v12, 16, v3
	v_and_b32_e32 v13, s33, v3
	v_lshlrev_b32_e32 v14, 16, v147
	v_and_b32_e32 v15, s33, v147
	v_lshlrev_b32_e32 v48, 16, v4
	v_and_b32_e32 v49, s33, v4
	v_lshlrev_b32_e32 v50, 16, v148
	v_and_b32_e32 v51, s33, v148
	v_lshlrev_b32_e32 v52, 16, v5
	v_and_b32_e32 v53, s33, v5
	v_lshlrev_b32_e32 v54, 16, v149
	v_and_b32_e32 v55, s33, v149
	s_waitcnt lgkmcnt(0)
	v_pk_fma_f32 v[8:9], v[6:7], v[10:11], v[8:9] op_sel_hi:[0,1,1]
	v_pk_fma_f32 v[12:13], v[6:7], v[14:15], v[12:13] op_sel_hi:[0,1,1]
	v_pk_fma_f32 v[48:49], v[6:7], v[50:51], v[48:49] op_sel_hi:[0,1,1]
	v_pk_fma_f32 v[52:53], v[6:7], v[54:55], v[52:53] op_sel_hi:[0,1,1]
	v_cvt_pk_bf16_f32 v2, v8, v9
	v_cvt_pk_bf16_f32 v3, v12, v13
	v_cvt_pk_bf16_f32 v4, v48, v49
	v_cvt_pk_bf16_f32 v5, v52, v53
.LBB0_225:
	v_or_b32_e32 v1, s25, v188
	v_lshlrev_b32_e32 v1, s43, v1
	v_add_u32_e32 v1, s6, v1
	v_lshl_add_u32 v6, v1, 10, v80
	v_mov_b32_e32 v7, v0
	v_lshl_add_u64 v[6:7], v[6:7], 1, s[88:89]
	s_waitcnt lgkmcnt(0)
	global_store_dwordx4 v[6:7], v[2:5], off sc1
	s_nop 1
	ds_read_b128 v[2:5], v209
	s_and_b64 vcc, exec, s[74:75]
	s_cbranch_vccnz .LBB0_227
	ds_read_b32 v6, v187 offset:192
	s_waitcnt lgkmcnt(1)
	s_waitcnt vmcnt(2)
	v_lshlrev_b32_e32 v8, 16, v2
	v_and_b32_e32 v9, s33, v2
	v_lshlrev_b32_e32 v10, 16, v158
	v_and_b32_e32 v11, s33, v158
	v_lshlrev_b32_e32 v12, 16, v3
	v_and_b32_e32 v13, s33, v3
	v_lshlrev_b32_e32 v14, 16, v159
	v_and_b32_e32 v15, s33, v159
	v_lshlrev_b32_e32 v48, 16, v4
	v_and_b32_e32 v49, s33, v4
	v_lshlrev_b32_e32 v50, 16, v160
	v_and_b32_e32 v51, s33, v160
	v_lshlrev_b32_e32 v52, 16, v5
	v_and_b32_e32 v53, s33, v5
	v_lshlrev_b32_e32 v54, 16, v161
	v_and_b32_e32 v55, s33, v161
	s_waitcnt lgkmcnt(0)
	v_pk_fma_f32 v[8:9], v[6:7], v[10:11], v[8:9] op_sel_hi:[0,1,1]
	v_pk_fma_f32 v[12:13], v[6:7], v[14:15], v[12:13] op_sel_hi:[0,1,1]
	v_pk_fma_f32 v[48:49], v[6:7], v[50:51], v[48:49] op_sel_hi:[0,1,1]
	v_pk_fma_f32 v[52:53], v[6:7], v[54:55], v[52:53] op_sel_hi:[0,1,1]
	v_cvt_pk_bf16_f32 v2, v8, v9
	v_cvt_pk_bf16_f32 v3, v12, v13
	v_cvt_pk_bf16_f32 v4, v48, v49
	v_cvt_pk_bf16_f32 v5, v52, v53
.LBB0_227:
	v_or_b32_e32 v1, s25, v189
	v_lshlrev_b32_e32 v1, s43, v1
	v_add_u32_e32 v1, s6, v1
	v_lshl_add_u32 v6, v1, 10, v80
	v_mov_b32_e32 v7, v0
	v_lshl_add_u64 v[6:7], v[6:7], 1, s[88:89]
	s_waitcnt lgkmcnt(0)
	global_store_dwordx4 v[6:7], v[2:5], off sc1
	s_nop 1
	ds_read_b128 v[2:5], v220
	s_and_b64 vcc, exec, s[74:75]
	s_cbranch_vccnz .LBB0_229
	ds_read_b32 v6, v187 offset:224
	s_waitcnt lgkmcnt(1)
	s_waitcnt vmcnt(1)
	v_lshlrev_b32_e32 v8, 16, v2
	v_and_b32_e32 v9, s33, v2
	v_lshlrev_b32_e32 v10, 16, v154
	v_and_b32_e32 v11, s33, v154
	v_lshlrev_b32_e32 v12, 16, v3
	v_and_b32_e32 v13, s33, v3
	v_lshlrev_b32_e32 v14, 16, v155
	v_and_b32_e32 v15, s33, v155
	v_lshlrev_b32_e32 v48, 16, v4
	v_and_b32_e32 v49, s33, v4
	v_lshlrev_b32_e32 v50, 16, v156
	v_and_b32_e32 v51, s33, v156
	v_lshlrev_b32_e32 v52, 16, v5
	v_and_b32_e32 v53, s33, v5
	v_lshlrev_b32_e32 v54, 16, v157
	v_and_b32_e32 v55, s33, v157
	s_waitcnt lgkmcnt(0)
	v_pk_fma_f32 v[8:9], v[6:7], v[10:11], v[8:9] op_sel_hi:[0,1,1]
	v_pk_fma_f32 v[12:13], v[6:7], v[14:15], v[12:13] op_sel_hi:[0,1,1]
	v_pk_fma_f32 v[48:49], v[6:7], v[50:51], v[48:49] op_sel_hi:[0,1,1]
	v_pk_fma_f32 v[52:53], v[6:7], v[54:55], v[52:53] op_sel_hi:[0,1,1]
	v_cvt_pk_bf16_f32 v2, v8, v9
	v_cvt_pk_bf16_f32 v3, v12, v13
	v_cvt_pk_bf16_f32 v4, v48, v49
	v_cvt_pk_bf16_f32 v5, v52, v53
